# one static priority raise (s_setprio 1) for waves 0-3 across the GEMM phases, per-phase setprio flips replaced by s_nop 0
# speedup vs baseline: 1.0105x; 1.0105x over previous
.LBB0_116:
	s_or_b64 exec, exec, s[4:5]
	s_mov_b64 s[0:1], s[86:87]
	s_waitcnt lgkmcnt(0)
	s_barrier
	v_readfirstlane_b32 s101, v204
	s_nop 3
	s_lshr_b32 s101, s101, 6
	s_cmp_lt_u32 s101, 4
	s_cbranch_scc0 .Lprio_0
	s_setprio 1

.LBB0_882:
	s_or_b64 exec, exec, s[4:5]
	v_readlane_b32 s4, v238, 16
	v_readlane_b32 s5, v238, 17
	s_waitcnt lgkmcnt(0)
	s_barrier
	v_readfirstlane_b32 s101, v204
	s_nop 3
	s_lshr_b32 s101, s101, 6
	s_cmp_lt_u32 s101, 4
	s_cbranch_scc0 .Lprio_1
	s_setprio 1

.LBB0_972:
	s_or_b64 exec, exec, s[6:7]
	v_readlane_b32 s0, v238, 16
	v_readlane_b32 s1, v238, 17
	s_waitcnt lgkmcnt(0)
	s_barrier
	v_readfirstlane_b32 s101, v204
	s_nop 3
	s_lshr_b32 s101, s101, 6
	s_cmp_lt_u32 s101, 4
	s_cbranch_scc0 .Lprio_2
	s_setprio 1

.LBB0_1044:
	s_or_b64 exec, exec, s[8:9]
	v_readlane_b32 s0, v238, 16
	v_readlane_b32 s1, v238, 17
	s_waitcnt lgkmcnt(0)
	s_barrier
	v_readfirstlane_b32 s101, v204
	s_nop 3
	s_lshr_b32 s101, s101, 6
	s_cmp_lt_u32 s101, 4
	s_cbranch_scc0 .Lprio_3
	s_setprio 1

.LBB0_1876:
	s_or_b64 exec, exec, s[8:9]
	s_mov_b64 s[8:9], s[70:71]
	v_mov_b32_e32 v8, v204
	s_waitcnt lgkmcnt(0)
	s_barrier
	v_readfirstlane_b32 s101, v204
	s_nop 3
	s_lshr_b32 s101, s101, 6
	s_cmp_lt_u32 s101, 4
	s_cbranch_scc0 .Lprio_5
	s_setprio 1

.LBB0_1966:
	s_or_b64 exec, exec, s[8:9]
	s_mov_b64 s[0:1], s[70:71]
	s_waitcnt lgkmcnt(0)
	s_barrier
	v_readfirstlane_b32 s101, v204
	s_nop 3
	s_lshr_b32 s101, s101, 6
	s_cmp_lt_u32 s101, 4
	s_cbranch_scc0 .Lprio_6
	s_setprio 1

.LBB0_2038:
	s_or_b64 exec, exec, s[6:7]
	s_mov_b64 s[0:1], s[70:71]
	s_waitcnt lgkmcnt(0)
	s_barrier
	v_readfirstlane_b32 s101, v204
	s_nop 3
	s_lshr_b32 s101, s101, 6
	s_cmp_lt_u32 s101, 4
	s_cbranch_scc0 .Lprio_7
	s_setprio 1
